# indexer: static priority raise for waves 4-7 removed (the batched appends and cached fragments changed the lockstep balance)
# speedup vs baseline: 1.0012x; 1.0012x over previous
; __device__ void indexer_item(LAS unsigned char* lds, const bf16_t* Qi, const bf16_t* Ki, const float* Wi, unsigned* maskout, int qt) {
;     ...
;     for (int i = 0; i < 4; ++i) { const int id = tid + 512 * i, row = id >> 7, ch = id & 127;
;         *(LAS u32x4*)(lds + row * IX_QP + ch * 16) = *(const GAS u32x4*)(Qi + (size_t)(t0 + row) * 1024 + ch * 8); }
;     if (tid < 64) cnt[tid] = 0u;
;     float wv[16];
; #pragma unroll
;     for (int i = 0; i < 4; ++i) { const f32x4 w4 = *(const GAS f32x4*)(Wi + (size_t)(t0 + q) * 16 + i * 4); wv[4 * i] = 0.5f * w4[0]; wv[4 * i + 1] = 0.5f * w4[1]; wv[4 * i + 2] = 0.5f * w4[2]; wv[4 * i + 3] = 0.5f * w4[3]; }
;     f32x4 wq[4];
; #pragma unroll
;     for (int i = 0; i < 4; ++i) wq[i] = *(const GAS f32x4*)(Wi + (size_t)(t0 + (tid >> 5)) * 16 + i * 4);
;     bf16x8 kn[2][2];
; #pragma unroll
;     for (int st = 0; st < 2; ++st)
; #pragma unroll
;         for (int ks = 0; ks < 2; ++ks) kn[st][ks] = *(const GAS bf16x8*)(Ki + (size_t)(wid * 32 + 16 * st + q) * 64 + ks * 32 + quad * 8);
; __global__ void __launch_bounds__(512, 2) mega(Params p_unused) {
;     ...
;         const Params p = load_params(kp); unsigned char* dout = (unsigned char*)p.out; unsigned* ctr = (unsigned*)(p.ws + WS_CTR); const int tid = opaque_tid();
;         int item;
;         FETCH_ITEM(0, 512);
;         if (item < 0) break;
;         const int qx = item >> 16, n = item & 0xFFFF;
;         if (n < 256) {
;             const int qb = 127 - (n >> 1), map = n & 1, b = qx & 1, hb = qx >> 1;
;             const size_t tok0 = (size_t)b * SEQ;
;             const bf16_t* Q = (const bf16_t*)(p.ws + WS_QB) + tok0 * 1024 + (hb * 2 + map) * 128;
;             const bf16_t* K = (const bf16_t*)(p.ws + WS_KB) + tok0 * 1024 + (hb * 2 + map) * 128;
;             const bf16_t* V = (const bf16_t*)(p.ws + WS_VB) + tok0 * 1024 + hb * 256;
;             bf16_t* O = (bf16_t*)(dout + DO_OB) + tok0 * 2048 + (hb * 2 + map) * 256;
;             attn_pair_block(lds, Q, K, V, qb, O, negMB_b);
;         } else {
;             const int i2 = (n - 256) * 8 + qx, qt = 1023 - (i2 >> 1), b = i2 & 1;
;             const size_t tok0 = (size_t)b * SEQ;
;             indexer_item(lds, (const bf16_t*)(p.ws + WS_QI) + tok0 * 1024, (const bf16_t*)(p.ws + WS_KI) + tok0 * 64, (const float*)(p.ws + WS_WI) + tok0 * 16,
;                          (unsigned*)(dout + DO_MASK) + tok0 * 512, qt);
.LBB0_624:
	s_or_b64 exec, exec, s[4:5]
	v_mov_b32_e32 v16, s53
	s_waitcnt lgkmcnt(0)
	s_barrier
	ds_read_b64 v[156:157], v16
	s_waitcnt lgkmcnt(0)
	v_readfirstlane_b32 s82, v156
	s_cmp_lt_i32 s82, 0
	s_cbranch_scc1 .LBB0_632
	s_lshr_b32 s84, s82, 16
	s_and_b32 s83, s82, 0xffff
	s_cmpk_gt_u32 s83, 0xff
	s_mov_b64 s[4:5], -1
	s_cbranch_scc0 .LBB0_803
	s_lshl_b32 s4, s84, 14
	s_and_b32 s6, s4, 0x4000
	s_lshl_b32 s85, s6, 11
	s_add_u32 s4, s50, s85
	s_addc_u32 s5, s51, 0
	s_lshl_b32 s7, s83, 6
	s_lshl_b32 s8, s84, 3
	v_mov_b32_e32 v59, v214
	s_add_i32 s7, s8, s7
	s_addk_i32 s7, 0xc000
	v_lshlrev_b32_e32 v16, 4, v59
	s_and_b32 s8, s7, -16
	v_and_b32_e32 v154, 0x7f0, v16
	s_sub_i32 s86, 0x3ff0, s8
	v_lshl_add_u64 v[16:17], s[4:5], 0, v[154:155]
	s_mov_b64 s[4:5], 0x14600000
	v_ashrrev_i32_e32 v36, 7, v59
	v_lshl_add_u64 v[24:25], v[16:17], 0, s[4:5]
	v_add_u32_e32 v16, s86, v36
	v_ashrrev_i32_e32 v17, 31, v16
	v_add_u32_e32 v70, 0x200, v59
	v_lshlrev_b64 v[16:17], 11, v[16:17]
	v_ashrrev_i32_e32 v37, 7, v70
	v_lshl_add_u64 v[26:27], v[24:25], 0, v[16:17]
	v_add_u32_e32 v16, s86, v37
	v_ashrrev_i32_e32 v17, 31, v16
	v_add_u32_e32 v72, 0x400, v59
	v_lshlrev_b64 v[16:17], 11, v[16:17]
	v_ashrrev_i32_e32 v38, 7, v72
	v_lshl_add_u64 v[28:29], v[24:25], 0, v[16:17]
	global_load_dwordx4 v[16:19], v[26:27], off
	global_load_dwordx4 v[20:23], v[28:29], off
	v_add_u32_e32 v26, s86, v38
	v_ashrrev_i32_e32 v27, 31, v26
	v_add_u32_e32 v71, 0x600, v59
	v_lshlrev_b64 v[26:27], 11, v[26:27]
	v_ashrrev_i32_e32 v40, 7, v71
	v_lshl_add_u64 v[32:33], v[24:25], 0, v[26:27]
	v_add_u32_e32 v26, s86, v40
	v_ashrrev_i32_e32 v27, 31, v26
	v_lshlrev_b64 v[26:27], 11, v[26:27]
	v_lshl_add_u64 v[34:35], v[24:25], 0, v[26:27]
	global_load_dwordx4 v[24:27], v[32:33], off
	global_load_dwordx4 v[28:31], v[34:35], off
	v_add_u32_e32 v32, 0, v154
	v_readfirstlane_b32 s9, v59
	v_mad_u64_u32 v[34:35], s[4:5], v36, s72, v[32:33]
	v_mad_u64_u32 v[36:37], s[4:5], v37, s72, v[32:33]
	v_mad_u64_u32 v[38:39], s[4:5], v38, s72, v[32:33]
	v_mad_u64_u32 v[32:33], s[4:5], v40, s72, v[32:33]
	v_cmp_gt_i32_e32 vcc, 64, v59
	s_waitcnt vmcnt(3)
	ds_write_b128 v34, v[16:19]
	s_waitcnt vmcnt(2)
	ds_write_b128 v36, v[20:23]
	s_waitcnt vmcnt(1)
	ds_write_b128 v38, v[24:27]
	s_waitcnt vmcnt(0)
	ds_write_b128 v32, v[28:31]
	s_and_saveexec_b64 s[4:5], vcc
	v_lshl_add_u32 v16, v59, 2, 0
	v_add_u32_e32 v16, 0x18900, v16
	ds_write_b32 v16, v155
	s_or_b64 exec, exec, s[4:5]
	s_lshl_b32 s4, s6, 7
	s_add_u32 s4, s50, s4
	s_addc_u32 s5, s51, 0
	s_lshl_b32 s6, s6, 6
	s_add_u32 s6, s50, s6
	v_ashrrev_i32_e32 v18, 5, v59
	s_addc_u32 s7, s51, 0
	v_add_u32_e32 v16, s86, v18
	s_add_u32 s6, s6, 0x18a00000
	v_ashrrev_i32_e32 v17, 31, v16
	s_addc_u32 s7, s7, 0
	v_lshlrev_b64 v[16:17], 6, v[16:17]
	v_lshl_add_u64 v[16:17], s[6:7], 0, v[16:17]
	global_load_dwordx4 v[48:51], v[16:17], off
	global_load_dwordx4 v[52:55], v[16:17], off offset:16
	global_load_dwordx4 v[64:67], v[16:17], off offset:32
	v_and_b32_e32 v73, 15, v59
	v_lshlrev_b32_e32 v19, 2, v59
	v_or_b32_e32 v56, s86, v73
	v_mul_lo_u32 v18, v18, s72
	v_and_b32_e32 v19, 0x7c, v19
	v_ashrrev_i32_e32 v57, 31, v56
	v_add3_u32 v58, 0, v18, v19
	v_lshlrev_b64 v[18:19], 6, v[56:57]
	v_lshl_add_u64 v[18:19], s[6:7], 0, v[18:19]
	global_load_dwordx4 v[74:77], v[16:17], off offset:48
	global_load_dwordx4 v[32:35], v[18:19], off offset:48
	global_load_dwordx4 v[36:39], v[18:19], off offset:32
	global_load_dwordx4 v[40:43], v[18:19], off offset:16
	global_load_dwordx4 v[44:47], v[18:19], off
	s_ashr_i32 s87, s9, 6
	s_lshl_b32 s6, s87, 5
	v_or_b32_e32 v62, s6, v73
	v_and_b32_e32 v154, 48, v59
	v_or_b32_e32 v16, 16, v62
	s_mov_b64 s[10:11], 0x18600000
	v_lshl_add_u64 v[20:21], s[4:5], 0, v[154:155]
	v_ashrrev_i32_e32 v63, 31, v62
	v_ashrrev_i32_e32 v17, 31, v16
	v_lshl_add_u64 v[60:61], v[20:21], 0, s[10:11]
	v_lshlrev_b64 v[18:19], 7, v[62:63]
	v_lshlrev_b64 v[22:23], 7, v[16:17]
	v_lshl_add_u64 v[20:21], v[60:61], 0, v[18:19]
	v_lshl_add_u64 v[68:69], v[60:61], 0, v[22:23]
	global_load_dwordx4 v[28:31], v[20:21], off
	global_load_dwordx4 v[16:19], v[20:21], off offset:64
	s_nop 0
	global_load_dwordx4 v[20:23], v[68:69], off
	global_load_dwordx4 v[24:27], v[68:69], off offset:64
	v_add_u32_e32 v57, 0x400, v58
	s_waitcnt lgkmcnt(0)
	s_barrier
; #define LAS __attribute__((address_space(3)))
; __device__ __forceinline__ unsigned cvt_pk_bf16(float lo, float hi) { unsigned r; asm volatile("v_cvt_pk_bf16_f32 %0, %1, %2" : "=v"(r) : "v"(lo), "v"(hi)); return r; }
; __device__ __forceinline__ float bflo(unsigned w) { return __uint_as_float(w << 16); }
; __device__ __forceinline__ float bfhi(unsigned w) { return __uint_as_float(w & 0xffff0000u); }
; __device__ void indexer_item(LAS unsigned char* lds, const bf16_t* Qi, const bf16_t* Ki, const float* Wi, unsigned* maskout, int qt) {
;     ...
;     {
;         const int qr = tid >> 5, dp = tid & 31;
;         float e0 = 0.f, e1 = 0.f;
; #pragma unroll
;         for (int i = 0; i < 4; ++i) { const f32x4 w4 = wq[i];
; #pragma unroll
;             for (int jj = 0; jj < 4; ++jj) { const unsigned v = *(const LAS unsigned*)(lds + qr * IX_QP + (4 * i + jj) * 128 + dp * 4); e0 += w4[jj] * bflo(v); e1 += w4[jj] * bfhi(v); } }
;         *(LAS unsigned*)(lds + qr * IX_QP + 16 * 128 + dp * 4) = cvt_pk_bf16(0.5f * e0, 0.5f * e1);
;     }
;     __syncthreads();
;     const int niter = (t0 + 16 + 255) >> 8;
;     const int tq = t0 + q;
;     const LAS unsigned char* qrow = lds + q * IX_QP + quad * 16;
;     unsigned thr = 0u;
;     if (wid >= 4) __builtin_amdgcn_s_setprio(1);
;     for (int it = 0; it < niter; ++it) {
	ds_read2_b32 v[68:69], v58 offset1:32
	ds_read2_b32 v[78:79], v58 offset0:64 offset1:96
	ds_read2_b32 v[80:81], v58 offset0:128 offset1:160
	ds_read2_b32 v[82:83], v58 offset0:192 offset1:224
	ds_read2_b32 v[84:85], v57 offset1:32
	ds_read2_b32 v[86:87], v57 offset0:64 offset1:96
	s_waitcnt lgkmcnt(5)
	v_lshlrev_b32_e32 v63, 16, v68
	v_and_b32_e32 v88, 0xffff0000, v68
	v_lshlrev_b32_e32 v89, 16, v69
	v_and_b32_e32 v90, 0xffff0000, v69
	s_waitcnt lgkmcnt(4)
	v_lshlrev_b32_e32 v91, 16, v78
	v_and_b32_e32 v92, 0xffff0000, v78
	v_lshlrev_b32_e32 v93, 16, v79
	v_and_b32_e32 v94, 0xffff0000, v79
	s_waitcnt lgkmcnt(3)
	v_lshlrev_b32_e32 v95, 16, v80
	v_and_b32_e32 v96, 0xffff0000, v80
	v_lshlrev_b32_e32 v97, 16, v81
	s_waitcnt lgkmcnt(2)
	v_lshlrev_b32_e32 v69, 16, v83
	v_lshlrev_b32_e32 v68, 16, v82
	v_and_b32_e32 v98, 0xffff0000, v81
	v_and_b32_e32 v79, 0xffff0000, v83
	v_and_b32_e32 v78, 0xffff0000, v82
	s_waitcnt lgkmcnt(1)
	v_lshlrev_b32_e32 v81, 16, v85
	v_lshlrev_b32_e32 v80, 16, v84
	v_and_b32_e32 v83, 0xffff0000, v85
	v_and_b32_e32 v82, 0xffff0000, v84
	s_cmp_lt_i32 s87, 4
	s_waitcnt vmcnt(11)
	v_fma_f32 v63, v48, v63, 0
	v_fma_f32 v48, v48, v88, 0
	v_fmac_f32_e32 v63, v49, v89
	v_fmac_f32_e32 v48, v49, v90
	v_fmac_f32_e32 v63, v50, v91
	v_fmac_f32_e32 v48, v50, v92
	v_fmac_f32_e32 v63, v51, v93
	v_fmac_f32_e32 v48, v51, v94
	s_waitcnt vmcnt(10)
	v_fmac_f32_e32 v63, v52, v95
	v_pk_mul_f32 v[68:69], v[54:55], v[68:69]
	v_fmac_f32_e32 v48, v52, v96
	v_fmac_f32_e32 v63, v53, v97
	v_pk_mul_f32 v[54:55], v[54:55], v[78:79]
	v_fmac_f32_e32 v48, v53, v98
	v_add_f32_e32 v49, v63, v68
	s_waitcnt vmcnt(9)
	v_pk_mul_f32 v[78:79], v[64:65], v[80:81]
	v_add_f32_e32 v48, v48, v54
	v_add_f32_e32 v49, v49, v69
	v_add_f32_e32 v50, v48, v55
	v_add_f32_e32 v48, v49, v78
	v_add_f32_e32 v51, v48, v79
	v_pk_mul_f32 v[48:49], v[64:65], v[82:83]
	s_nop 0
	v_add_f32_e32 v48, v50, v48
	v_add_f32_e32 v52, v48, v49
	s_waitcnt lgkmcnt(0)
	v_lshlrev_b32_e32 v49, 16, v87
	v_lshlrev_b32_e32 v48, 16, v86
	v_pk_mul_f32 v[48:49], v[66:67], v[48:49]
	s_nop 0
	v_add_f32_e32 v48, v51, v48
	ds_read2_b32 v[50:51], v57 offset0:128 offset1:160
	v_add_f32_e32 v53, v48, v49
	v_and_b32_e32 v49, 0xffff0000, v87
	v_and_b32_e32 v48, 0xffff0000, v86
	v_pk_mul_f32 v[48:49], v[66:67], v[48:49]
	s_nop 0
	v_add_f32_e32 v48, v52, v48
	v_add_f32_e32 v54, v48, v49
	s_waitcnt lgkmcnt(0)
	v_lshlrev_b32_e32 v49, 16, v51
	v_lshlrev_b32_e32 v48, 16, v50
	s_waitcnt vmcnt(8)
	v_pk_mul_f32 v[48:49], v[74:75], v[48:49]
	s_nop 0
	v_add_f32_e32 v48, v53, v48
	ds_read2_b32 v[52:53], v57 offset0:192 offset1:224
	v_add_f32_e32 v55, v48, v49
	v_and_b32_e32 v49, 0xffff0000, v51
	v_and_b32_e32 v48, 0xffff0000, v50
	v_pk_mul_f32 v[48:49], v[74:75], v[48:49]
	s_nop 0
	v_add_f32_e32 v48, v54, v48
	v_add_f32_e32 v50, v48, v49
	s_waitcnt lgkmcnt(0)
	v_lshlrev_b32_e32 v49, 16, v53
	v_lshlrev_b32_e32 v48, 16, v52
	v_pk_mul_f32 v[48:49], v[76:77], v[48:49]
	s_nop 0
	v_add_f32_e32 v48, v55, v48
	v_add_f32_e32 v51, v48, v49
	v_and_b32_e32 v49, 0xffff0000, v53
	v_and_b32_e32 v48, 0xffff0000, v52
	v_pk_mul_f32 v[48:49], v[76:77], v[48:49]
	s_nop 0
	v_add_f32_e32 v48, v50, v48
	v_add_f32_e32 v48, v48, v49
	v_mul_f32_e32 v48, 0.5, v48
	v_mul_f32_e32 v49, 0.5, v51
	v_cvt_pk_bf16_f32 v48, v49, v48
	ds_write_b32 v58, v48 offset:2048
	s_waitcnt lgkmcnt(0)
	s_barrier
	s_cbranch_scc1 .LBB0_630
.LBB0_630:
	v_and_b32_e32 v63, 63, v59
	s_sub_i32 s4, 0x40f0, s8
	s_ashr_i32 s89, s4, 8
	v_lshlrev_b64 v[48:49], v63, -1
	s_cmp_gt_i32 s89, 0
	v_or_b32_e32 v74, 64, v63
	v_or_b32_e32 v75, 0x80, v63
	v_or_b32_e32 v76, 0xc0, v63
	v_or_b32_e32 v77, 0x100, v63
	v_or_b32_e32 v78, 0x140, v63
	v_or_b32_e32 v79, 0x180, v63
	v_or_b32_e32 v80, 0x1c0, v63
	v_not_b32_e32 v57, v49
	v_not_b32_e32 v58, v48
	s_cbranch_scc1 .LBB0_633
	s_lshl_b32 s88, s87, 1
	v_or_b32_e32 v48, 64, v63
	v_or_b32_e32 v49, 0x80, v63
	v_or_b32_e32 v50, 0xc0, v63
	v_or_b32_e32 v51, 0x100, v63
	v_or_b32_e32 v52, 0x140, v63
	v_or_b32_e32 v53, 0x180, v63
	v_or_b32_e32 v54, 0x1c0, v63
	v_cmp_eq_u32_e64 s[4:5], 0, v63
	s_cbranch_execz .LBB0_634
	s_branch .LBB0_753
